# index phase xhalf merge extended to 36 of 40 sites (incl. in-place packed PASS2 form)
# baseline (speedup 1.0000x reference)
; DI void phase_index(const Params& p, unsigned char* lds) {
;     ...
;             const int key = k0 + 32 * kb + r32;
; #pragma unroll
;             for (int qq = 0; qq < 2; ++qq) {
;                 const float t_lo = tot[qq], t_hi = tot[2 + qq];
;                 const float sc = ((lane & 32) ? t_hi : t_lo) + 0.0f;
;                 const unsigned ub = __float_as_uint(sc);
;                 const unsigned uk = ub ^ ((unsigned)((int)ub >> 31) | 0x80000000u);
;                 const bool valid = DIAG ? (key <= tq0 + qq) : true;
;                 if (PASS == 0) {
;                     if (valid) { const unsigned a = (uk >> 21) & 0x7feu; atomicAdd((unsigned*)(lds + hbase0 + qq * 2048 + (a & ~3u)), 1u << ((a & 2u) << 3)); }
;                 } else if (PASS == 1) {
;                     if (valid && (int)(uk >> 22) == b1v[qq]) { const unsigned a = (uk >> 11) & 0x7feu; atomicAdd((unsigned*)(lds + hbase0 + qq * 2048 + (a & ~3u)), 1u << ((a & 2u) << 3)); }
;                 } else if (PASS == 3) {
;                     if (valid) {
;                         const int k10 = (int)(uk >> 22), d = k10 - b1v[qq];
;                         if (k10 > hiv[qq]) cntA[qq] += 1;
;                         else if (d >= 0) {
;                             const unsigned bin = ((unsigned)d << sbv[qq]) | ((uk >> (22 - sbv[qq])) & ((1u << sbv[qq]) - 1u));
;                             const unsigned a = bin << 1;
;                             atomicAdd((unsigned*)(lds + hbase0 + qq * 2048 + (a & ~3u)), 1u << ((a & 2u) << 3));
;                         }
;                     }
.LBB0_2682:
	v_permlane32_swap_b32_e32 v173, v174
	v_permlane32_swap_b32_e32 v170, v172
	v_cmp_le_i32_e32 vcc, v164, v95
	s_and_saveexec_b64 s[30:31], vcc
	s_cbranch_execz .LBB0_2690
	v_add_f32_e32 v173, v173, v174
	v_add_f32_e32 v173, 0, v173
	v_ashrrev_i32_e32 v174, 31, v173
	v_bitop3_b32 v173, v174, v173, s82 bitop3:0x36
	v_lshrrev_b32_e32 v174, 22, v173
	v_cmp_le_i32_e32 vcc, v174, v101
	s_and_saveexec_b64 s[34:35], vcc
	s_xor_b64 s[38:39], exec, s[34:35]
	s_cbranch_execz .LBB0_2687
	v_sub_u32_e32 v174, v174, v100
	v_cmp_lt_i32_e32 vcc, -1, v174
	s_and_saveexec_b64 s[50:51], vcc
	s_cbranch_execz .LBB0_2686
	v_lshrrev_b32_e32 v173, v113, v173
	v_and_b32_e32 v173, v173, v114
	v_lshl_or_b32 v173, v174, v111, v173
	v_lshlrev_b32_e32 v174, 1, v173
	v_and_b32_e32 v174, -4, v174
	v_lshlrev_b32_e32 v173, 4, v173
	v_add_u32_e32 v174, v123, v174
	v_lshlrev_b32_e64 v173, v173, 1
	ds_add_u32 v174, v173

; DI void phase_index(const Params& p, unsigned char* lds) {
;     ...
;                 } else if (PASS == 3) {
;                     if (valid) {
;                         const int k10 = (int)(uk >> 22), d = k10 - b1v[qq];
;                         if (k10 > hiv[qq]) cntA[qq] += 1;
;                         else if (d >= 0) {
;                             const unsigned bin = ((unsigned)d << sbv[qq]) | ((uk >> (22 - sbv[qq])) & ((1u << sbv[qq]) - 1u));
;                             const unsigned a = bin << 1;
;                             atomicAdd((unsigned*)(lds + hbase0 + qq * 2048 + (a & ~3u)), 1u << ((a & 2u) << 3));
;                         }
;                     }
.LBB0_2690:
	s_or_b64 exec, exec, s[30:31]
	v_cmp_le_i32_e32 vcc, v164, v117
	s_and_saveexec_b64 s[30:31], vcc
	s_cbranch_execz .LBB0_2698
	v_add_f32_e32 v167, v170, v172
	v_add_f32_e32 v167, 0, v167
	v_ashrrev_i32_e32 v169, 31, v167
	v_bitop3_b32 v167, v169, v167, s82 bitop3:0x36
	v_lshrrev_b32_e32 v169, 22, v167
	v_cmp_le_i32_e32 vcc, v169, v103
	s_and_saveexec_b64 s[34:35], vcc
	s_xor_b64 s[38:39], exec, s[34:35]
	s_cbranch_execz .LBB0_2695
	v_sub_u32_e32 v169, v169, v102
	v_cmp_lt_i32_e32 vcc, -1, v169
	s_and_saveexec_b64 s[50:51], vcc
	s_cbranch_execz .LBB0_2694
	v_lshrrev_b32_e32 v167, v115, v167
	v_and_b32_e32 v167, v167, v116
	v_lshl_or_b32 v167, v169, v112, v167
	v_lshlrev_b32_e32 v169, 1, v167
	v_and_b32_e32 v169, -4, v169
	v_lshlrev_b32_e32 v167, 4, v167
	v_add_u32_e32 v169, v123, v169
	v_lshlrev_b32_e64 v167, v167, 1
	ds_add_u32 v169, v167 offset:2048

; DI void phase_index(const Params& p, unsigned char* lds) {
;     ...
;             const int key = k0 + 32 * kb + r32;
; #pragma unroll
;             for (int qq = 0; qq < 2; ++qq) {
;                 const float t_lo = tot[qq], t_hi = tot[2 + qq];
;                 const float sc = ((lane & 32) ? t_hi : t_lo) + 0.0f;
;                 const unsigned ub = __float_as_uint(sc);
;                 const unsigned uk = ub ^ ((unsigned)((int)ub >> 31) | 0x80000000u);
;                 const bool valid = DIAG ? (key <= tq0 + qq) : true;
;                 if (PASS == 0) {
;                     if (valid) { const unsigned a = (uk >> 21) & 0x7feu; atomicAdd((unsigned*)(lds + hbase0 + qq * 2048 + (a & ~3u)), 1u << ((a & 2u) << 3)); }
;                 } else if (PASS == 1) {
;                     if (valid && (int)(uk >> 22) == b1v[qq]) { const unsigned a = (uk >> 11) & 0x7feu; atomicAdd((unsigned*)(lds + hbase0 + qq * 2048 + (a & ~3u)), 1u << ((a & 2u) << 3)); }
;                 } else if (PASS == 3) {
;                     if (valid) {
;                         const int k10 = (int)(uk >> 22), d = k10 - b1v[qq];
;                         if (k10 > hiv[qq]) cntA[qq] += 1;
;                         else if (d >= 0) {
;                             const unsigned bin = ((unsigned)d << sbv[qq]) | ((uk >> (22 - sbv[qq])) & ((1u << sbv[qq]) - 1u));
;                             const unsigned a = bin << 1;
;                             atomicAdd((unsigned*)(lds + hbase0 + qq * 2048 + (a & ~3u)), 1u << ((a & 2u) << 3));
;                         }
;                     }
;                 } else {
;                     const int k20 = (int)(uk >> kshv[qq]);
;                     const u64 bg = __ballot(valid && k20 > tauv[qq]);
;                     const u64 be = __ballot(valid && k20 == tauv[qq]);
;                     Gm[qq] |= (bg & 0xffffffffull) << (32 * kb); Gm[2 + qq] |= (bg >> 32) << (32 * kb);
;                     Em[qq] |= (be & 0xffffffffull) << (32 * kb); Em[2 + qq] |= (be >> 32) << (32 * kb);
;                 }
.LBB0_3526:
	s_andn2_b64 vcc, exec, s[28:29]
	s_cbranch_vccnz .LBB0_3528
	v_permlane32_swap_b32_e32 v18, v20
	v_permlane32_swap_b32_e32 v19, v21
	v_pk_add_f32 v[18:19], v[18:19], v[20:21]
	v_or_b32_e32 v26, 32, v164
	v_pk_add_f32 v[18:19], v[18:19], 0 op_sel_hi:[1,0]
	v_cmp_le_i32_e32 vcc, v26, v95
	v_ashrrev_i32_e32 v21, 31, v18
	v_ashrrev_i32_e32 v20, 31, v19
	v_or_b32_e32 v21, 0x80000000, v21
	v_or_b32_e32 v20, 0x80000000, v20
	v_xor_b32_e32 v18, v21, v18
	v_xor_b32_e32 v19, v20, v19
	v_lshrrev_b32_e32 v18, v106, v18
	v_add_u32_e32 v26, 31, v164
	v_lshrrev_b32_e32 v19, v83, v19
	v_cmp_gt_i32_e64 s[28:29], v18, v100
	v_cmp_eq_u32_e64 s[30:31], v18, v100
	v_cmp_le_i32_e64 s[26:27], v26, v95
	s_and_b64 s[28:29], vcc, s[28:29]
	s_and_b64 s[30:31], vcc, s[30:31]
	v_cmp_gt_i32_e32 vcc, v19, v1
	v_cndmask_b32_e64 v20, 0, 1, s[28:29]
	v_cmp_eq_u32_e64 s[28:29], v19, v1
	v_cndmask_b32_e64 v18, 0, 1, s[30:31]
	s_and_b64 s[30:31], s[26:27], vcc
	v_cmp_ne_u32_e64 s[68:69], 0, v18
	v_cndmask_b32_e64 v18, 0, 1, s[30:31]
	s_and_b64 s[26:27], s[26:27], s[28:29]
	v_cmp_ne_u32_e64 s[30:31], 0, v18
	v_cndmask_b32_e64 v18, 0, 1, s[26:27]
	v_cmp_ne_u32_e64 s[58:59], 0, v20
	v_cmp_ne_u32_e64 s[26:27], 0, v18

; DI void phase_index(const Params& p, unsigned char* lds) {
;     ...
;             const int key = k0 + 32 * kb + r32;
; #pragma unroll
;             for (int qq = 0; qq < 2; ++qq) {
;                 const float t_lo = tot[qq], t_hi = tot[2 + qq];
;                 const float sc = ((lane & 32) ? t_hi : t_lo) + 0.0f;
;                 const unsigned ub = __float_as_uint(sc);
;                 const unsigned uk = ub ^ ((unsigned)((int)ub >> 31) | 0x80000000u);
;                 const bool valid = DIAG ? (key <= tq0 + qq) : true;
;                 if (PASS == 0) {
;                     if (valid) { const unsigned a = (uk >> 21) & 0x7feu; atomicAdd((unsigned*)(lds + hbase0 + qq * 2048 + (a & ~3u)), 1u << ((a & 2u) << 3)); }
;                 } else if (PASS == 1) {
;                     if (valid && (int)(uk >> 22) == b1v[qq]) { const unsigned a = (uk >> 11) & 0x7feu; atomicAdd((unsigned*)(lds + hbase0 + qq * 2048 + (a & ~3u)), 1u << ((a & 2u) << 3)); }
;                 } else if (PASS == 3) {
;                     if (valid) {
;                         const int k10 = (int)(uk >> 22), d = k10 - b1v[qq];
;                         if (k10 > hiv[qq]) cntA[qq] += 1;
;                         else if (d >= 0) {
;                             const unsigned bin = ((unsigned)d << sbv[qq]) | ((uk >> (22 - sbv[qq])) & ((1u << sbv[qq]) - 1u));
;                             const unsigned a = bin << 1;
;                             atomicAdd((unsigned*)(lds + hbase0 + qq * 2048 + (a & ~3u)), 1u << ((a & 2u) << 3));
;                         }
;                     }
;                 } else {
;                     const int k20 = (int)(uk >> kshv[qq]);
;                     const u64 bg = __ballot(valid && k20 > tauv[qq]);
;                     const u64 be = __ballot(valid && k20 == tauv[qq]);
;                     Gm[qq] |= (bg & 0xffffffffull) << (32 * kb); Gm[2 + qq] |= (bg >> 32) << (32 * kb);
;                     Em[qq] |= (be & 0xffffffffull) << (32 * kb); Em[2 + qq] |= (be >> 32) << (32 * kb);
;                 }
.LBB0_3556:
	v_permlane32_swap_b32_e32 v114, v116
	v_permlane32_swap_b32_e32 v115, v117
	v_pk_add_f32 v[114:115], v[114:115], v[116:117]
	v_cmp_le_i32_e32 vcc, v164, v95
	v_pk_add_f32 v[114:115], v[114:115], 0 op_sel_hi:[1,0]
	v_cmp_le_i32_e64 s[26:27], v164, v101
	v_ashrrev_i32_e32 v117, 31, v114
	v_ashrrev_i32_e32 v116, 31, v115
	v_or_b32_e32 v117, 0x80000000, v117
	v_or_b32_e32 v116, 0x80000000, v116
	v_xor_b32_e32 v114, v117, v114
	v_xor_b32_e32 v115, v116, v115
	v_lshrrev_b32_e32 v114, v106, v114
	v_lshrrev_b32_e32 v115, v83, v115
	v_cmp_gt_i32_e64 s[28:29], v114, v100
	v_cmp_eq_u32_e64 s[30:31], v114, v100
	s_and_b64 s[28:29], vcc, s[28:29]
	s_and_b64 s[30:31], vcc, s[30:31]
	v_cmp_gt_i32_e32 vcc, v115, v1
	v_cndmask_b32_e64 v116, 0, 1, s[28:29]
	v_cmp_eq_u32_e64 s[28:29], v115, v1
	v_cndmask_b32_e64 v114, 0, 1, s[30:31]
	s_and_b64 s[30:31], s[26:27], vcc
	v_cmp_ne_u32_e64 s[56:57], 0, v114
	v_cndmask_b32_e64 v114, 0, 1, s[30:31]
	s_and_b64 s[26:27], s[26:27], s[28:29]
	v_cmp_ne_u32_e64 s[50:51], 0, v114
	v_cndmask_b32_e64 v114, 0, 1, s[26:27]
	v_cmp_ne_u32_e64 s[52:53], 0, v116
	v_cmp_ne_u32_e64 s[54:55], 0, v114
	s_add_i32 s1, s1, 1
	s_cmp_ge_i32 s1, s97
	s_cbranch_scc0 .LBB0_3523
	s_branch .LBB0_3524
